# P1 stream split: converter workgroups run their idle-tail w_out conversion after 1..11 units (staggered) then re-enter the stream
# baseline (speedup 1.0000x reference)
.LBB0_202:
	v_readlane_b32 s0, v254, 16
	s_nop 3
	s_lshl_b32 s0, s0, 10
	s_add_i32 s0, s0, 0x21400
	s_nop 1
	v_mov_b32_e32 v0, s0
	v_mov_b32_e32 v1, s0
	ds_write_b32 v0, v1 offset:0
	v_mov_b32_e32 v5, s1
	ds_write_b32 v0, v5 offset:4
	v_mov_b32_e32 v1, s2
	ds_write_b32 v0, v1 offset:8
	v_mov_b32_e32 v5, s3
	ds_write_b32 v0, v5 offset:12
	v_mov_b32_e32 v1, s4
	ds_write_b32 v0, v1 offset:16
	v_mov_b32_e32 v5, s5
	ds_write_b32 v0, v5 offset:20
	v_mov_b32_e32 v1, s6
	ds_write_b32 v0, v1 offset:24
	v_mov_b32_e32 v5, s7
	ds_write_b32 v0, v5 offset:28
	v_mov_b32_e32 v1, s8
	ds_write_b32 v0, v1 offset:32
	v_mov_b32_e32 v5, s9
	ds_write_b32 v0, v5 offset:36
	v_mov_b32_e32 v1, s10
	ds_write_b32 v0, v1 offset:40
	v_mov_b32_e32 v5, s11
	ds_write_b32 v0, v5 offset:44
	v_mov_b32_e32 v1, s12
	ds_write_b32 v0, v1 offset:48
	v_mov_b32_e32 v5, s13
	ds_write_b32 v0, v5 offset:52
	v_mov_b32_e32 v1, s14
	ds_write_b32 v0, v1 offset:56
	v_mov_b32_e32 v5, s15
	ds_write_b32 v0, v5 offset:60
	v_mov_b32_e32 v1, s16
	ds_write_b32 v0, v1 offset:64
	v_mov_b32_e32 v5, s17
	ds_write_b32 v0, v5 offset:68
	v_mov_b32_e32 v1, s18
	ds_write_b32 v0, v1 offset:72
	v_mov_b32_e32 v5, s19
	ds_write_b32 v0, v5 offset:76
	v_mov_b32_e32 v1, s20
	ds_write_b32 v0, v1 offset:80
	v_mov_b32_e32 v5, s21
	ds_write_b32 v0, v5 offset:84
	v_mov_b32_e32 v1, s22
	ds_write_b32 v0, v1 offset:88
	v_mov_b32_e32 v5, s23
	ds_write_b32 v0, v5 offset:92
	v_mov_b32_e32 v1, s24
	ds_write_b32 v0, v1 offset:96
	v_mov_b32_e32 v5, s25
	ds_write_b32 v0, v5 offset:100
	v_mov_b32_e32 v1, s26
	ds_write_b32 v0, v1 offset:104
	v_mov_b32_e32 v5, s27
	ds_write_b32 v0, v5 offset:108
	v_mov_b32_e32 v1, s28
	ds_write_b32 v0, v1 offset:112
	v_mov_b32_e32 v5, s29
	ds_write_b32 v0, v5 offset:116
	v_mov_b32_e32 v1, s30
	ds_write_b32 v0, v1 offset:120
	v_mov_b32_e32 v5, s31
	ds_write_b32 v0, v5 offset:124
	v_mov_b32_e32 v1, s32
	ds_write_b32 v0, v1 offset:128
	v_mov_b32_e32 v5, s33
	ds_write_b32 v0, v5 offset:132
	v_mov_b32_e32 v1, s34
	ds_write_b32 v0, v1 offset:136
	v_mov_b32_e32 v5, s35
	ds_write_b32 v0, v5 offset:140
	v_mov_b32_e32 v1, s36
	ds_write_b32 v0, v1 offset:144
	v_mov_b32_e32 v5, s37
	ds_write_b32 v0, v5 offset:148
	v_mov_b32_e32 v1, s38
	ds_write_b32 v0, v1 offset:152
	v_mov_b32_e32 v5, s39
	ds_write_b32 v0, v5 offset:156
	v_mov_b32_e32 v1, s40
	ds_write_b32 v0, v1 offset:160
	v_mov_b32_e32 v5, s41
	ds_write_b32 v0, v5 offset:164
	v_mov_b32_e32 v1, s42
	ds_write_b32 v0, v1 offset:168
	v_mov_b32_e32 v5, s43
	ds_write_b32 v0, v5 offset:172
	v_mov_b32_e32 v1, s44
	ds_write_b32 v0, v1 offset:176
	v_mov_b32_e32 v5, s45
	ds_write_b32 v0, v5 offset:180
	v_mov_b32_e32 v1, s46
	ds_write_b32 v0, v1 offset:184
	v_mov_b32_e32 v5, s47
	ds_write_b32 v0, v5 offset:188
	v_mov_b32_e32 v1, s48
	ds_write_b32 v0, v1 offset:192
	v_mov_b32_e32 v5, s49
	ds_write_b32 v0, v5 offset:196
	v_mov_b32_e32 v1, s50
	ds_write_b32 v0, v1 offset:200
	v_mov_b32_e32 v5, s51
	ds_write_b32 v0, v5 offset:204
	v_mov_b32_e32 v1, s52
	ds_write_b32 v0, v1 offset:208
	v_mov_b32_e32 v5, s53
	ds_write_b32 v0, v5 offset:212
	v_mov_b32_e32 v1, s54
	ds_write_b32 v0, v1 offset:216
	v_mov_b32_e32 v5, s55
	ds_write_b32 v0, v5 offset:220
	v_mov_b32_e32 v1, s56
	ds_write_b32 v0, v1 offset:224
	v_mov_b32_e32 v5, s57
	ds_write_b32 v0, v5 offset:228
	v_mov_b32_e32 v1, s58
	ds_write_b32 v0, v1 offset:232
	v_mov_b32_e32 v5, s59
	ds_write_b32 v0, v5 offset:236
	v_mov_b32_e32 v1, s60
	ds_write_b32 v0, v1 offset:240
	v_mov_b32_e32 v5, s61
	ds_write_b32 v0, v5 offset:244
	v_mov_b32_e32 v1, s62
	ds_write_b32 v0, v1 offset:248
	v_mov_b32_e32 v5, s63
	ds_write_b32 v0, v5 offset:252
	v_mov_b32_e32 v1, s64
	ds_write_b32 v0, v1 offset:256
	v_mov_b32_e32 v5, s65
	ds_write_b32 v0, v5 offset:260
	v_mov_b32_e32 v1, s66
	ds_write_b32 v0, v1 offset:264
	v_mov_b32_e32 v5, s67
	ds_write_b32 v0, v5 offset:268
	v_mov_b32_e32 v1, s68
	ds_write_b32 v0, v1 offset:272
	v_mov_b32_e32 v5, s69
	ds_write_b32 v0, v5 offset:276
	v_mov_b32_e32 v1, s70
	ds_write_b32 v0, v1 offset:280
	v_mov_b32_e32 v5, s71
	ds_write_b32 v0, v5 offset:284
	v_mov_b32_e32 v1, s72
	ds_write_b32 v0, v1 offset:288
	v_mov_b32_e32 v5, s73
	ds_write_b32 v0, v5 offset:292
	v_mov_b32_e32 v1, s74
	ds_write_b32 v0, v1 offset:296
	v_mov_b32_e32 v5, s75
	ds_write_b32 v0, v5 offset:300
	v_mov_b32_e32 v1, s76
	ds_write_b32 v0, v1 offset:304
	v_mov_b32_e32 v5, s77
	ds_write_b32 v0, v5 offset:308
	v_mov_b32_e32 v1, s78
	ds_write_b32 v0, v1 offset:312
	v_mov_b32_e32 v5, s79
	ds_write_b32 v0, v5 offset:316
	v_mov_b32_e32 v1, s80
	ds_write_b32 v0, v1 offset:320
	v_mov_b32_e32 v5, s81
	ds_write_b32 v0, v5 offset:324
	v_mov_b32_e32 v1, s82
	ds_write_b32 v0, v1 offset:328
	v_mov_b32_e32 v5, s83
	ds_write_b32 v0, v5 offset:332
	v_mov_b32_e32 v1, s84
	ds_write_b32 v0, v1 offset:336
	v_mov_b32_e32 v5, s85
	ds_write_b32 v0, v5 offset:340
	v_mov_b32_e32 v1, s86
	ds_write_b32 v0, v1 offset:344
	v_mov_b32_e32 v5, s87
	ds_write_b32 v0, v5 offset:348
	v_mov_b32_e32 v1, s88
	ds_write_b32 v0, v1 offset:352
	v_mov_b32_e32 v5, s89
	ds_write_b32 v0, v5 offset:356
	v_mov_b32_e32 v1, s90
	ds_write_b32 v0, v1 offset:360
	v_mov_b32_e32 v5, s91
	ds_write_b32 v0, v5 offset:364
	v_mov_b32_e32 v1, s92
	ds_write_b32 v0, v1 offset:368
	v_mov_b32_e32 v5, s93
	ds_write_b32 v0, v5 offset:372
	v_mov_b32_e32 v1, s94
	ds_write_b32 v0, v1 offset:376
	v_mov_b32_e32 v5, s95
	ds_write_b32 v0, v5 offset:380
	v_mov_b32_e32 v1, s96
	ds_write_b32 v0, v1 offset:384
	v_mov_b32_e32 v5, s97
	ds_write_b32 v0, v5 offset:388
	v_mov_b32_e32 v1, vcc_lo
	ds_write_b32 v0, v1 offset:408
	v_mov_b32_e32 v5, vcc_hi
	ds_write_b32 v0, v5 offset:412
	v_mbcnt_lo_u32_b32 v2, -1, 0
	v_mbcnt_hi_u32_b32 v2, -1, v2
	v_lshl_add_u32 v2, v2, 2, v0
	ds_write_b32 v2, v254 offset:512
	ds_write_b32 v2, v255 offset:768
	s_mov_b32 s0, 1
	s_movk_i32 s1, 0
	s_movk_i32 s2, 0xb6c
	s_cmpk_lg_i32 s33, 0x100
	s_cbranch_scc1 .Lsplit_ctl_1
	s_sub_i32 s3, s95, 108
	s_cmp_lt_i32 s3, 0
	s_cbranch_scc1 .Lsplit_ctl_1
	s_mul_hi_u32 s0, s3, 0x1745d175
	s_mul_i32 s0, s0, 11
	s_sub_i32 s0, s3, s0
	s_add_i32 s0, s0, 1
	s_lshl_b32 s1, s0, 8
	s_mov_b32 s2, s1
	s_mov_b32 s0, 0
.Lsplit_ctl_1:
	v_readlane_b32 s3, v254, 16
	s_nop 3
	s_lshl_b32 s3, s3, 4
	s_add_i32 s3, s3, 0x23800
	s_nop 1
	v_mov_b32_e32 v1, s3
	v_mov_b32_e32 v2, s0
	v_mov_b32_e32 v5, s1
	ds_write_b32 v1, v2
	ds_write_b32 v1, v5 offset:4
	v_mov_b32_e32 v2, s2
	ds_write_b32 v1, v2 offset:8
	ds_read_b32 v1, v0 offset:0
	s_waitcnt lgkmcnt(0)
	v_readfirstlane_b32 s0, v1
	ds_read_b32 v1, v0 offset:4
	s_waitcnt lgkmcnt(0)
	v_readfirstlane_b32 s1, v1
	ds_read_b32 v1, v0 offset:8
	s_waitcnt lgkmcnt(0)
	v_readfirstlane_b32 s2, v1
	ds_read_b32 v1, v0 offset:12
	s_waitcnt lgkmcnt(0)
	v_readfirstlane_b32 s3, v1
	s_waitcnt lgkmcnt(0)
	s_nop 4

.LBB0_210:
	s_ashr_i32 s4, s12, 31
	s_lshr_b32 s4, s4, 26
	s_add_i32 s4, s12, s4
	s_ashr_i32 s49, s4, 6
	v_readlane_b32 s4, v254, 16
	s_lshl_b32 s4, s4, 5
	s_and_b32 s59, s4, 0x60
	s_lshl_b32 s58, s0, 6
	s_lshl_b32 s0, s0, 13
	s_lshr_b32 s4, s59, 3
	s_add_u32 s10, s34, 0xa0000
	s_addc_u32 s11, s35, 0
	s_add_i32 s60, s2, 0x18000
	s_or_b32 s5, s6, 0x80
	s_mov_b32 s30, s86
	s_mov_b32 s31, s87
	s_mov_b32 m0, s60
	s_add_i32 s61, s2, 0x1a000
	s_waitcnt vmcnt(2)
	s_barrier
	buffer_load_dwordx4 v145, s[28:31], s5 offen lds
	s_mov_b32 m0, s61
	s_add_i32 s70, s2, 0x8000
	buffer_load_dwordx4 v149, s[28:31], s5 offen lds
	s_or_b32 s5, s7, 0x80
	s_mov_b32 m0, s70
	s_add_i32 s71, s2, 0xa000
	buffer_load_dwordx4 v143, s[84:87], s5 offen lds
	s_mov_b32 m0, s71
	s_add_i32 s73, s2, 0x1c000
	buffer_load_dwordx4 v147, s[84:87], s5 offen lds
	s_or_b32 s5, s6, 0x80080
	s_mov_b32 m0, s73
	s_add_i32 s74, s2, 0x1e000
	buffer_load_dwordx4 v145, s[28:31], s5 offen lds
	s_mov_b32 m0, s74
	v_ashrrev_i32_e32 v1, 6, v0
	buffer_load_dwordx4 v149, s[28:31], s5 offen lds
	v_and_b32_e32 v2, 48, v0
	v_lshl_add_u32 v3, v1, 10, s0
	v_lshlrev_b32_e32 v4, 6, v0
	s_movk_i32 s0, 0x3c0
	s_cmp_gt_i32 s12, 63
	v_and_or_b32 v2, v4, s0, v2
	s_cselect_b64 s[12:13], -1, 0
	s_add_i32 s75, s49, -2
	s_add_i32 s78, s2, 0xc000
	v_readlane_b32 s0, v254, 20
	v_lshlrev_b32_e32 v0, 2, v0
	s_cmpk_lt_u32 s0, 0x100
	v_and_b32_e32 v0, 32, v0
	v_add_lshl_u32 v1, v1, s4, 10
	s_waitcnt vmcnt(6)
	s_cselect_b64 s[16:17], -1, 0
	s_add_i32 s79, s2, 0xe000
	s_ashr_i32 s80, s33, 31
	v_bitop3_b32 v3, v2, v3, v0 bitop3:0xde
	v_bitop3_b32 v0, v2, v1, v0 bitop3:0xde
	s_add_u32 s22, s34, 0x4ac00
	s_mov_b32 s54, 0x3c010204
	s_sext_i32_i16 s94, s1
	s_addc_u32 s23, s35, 0
	v_mov_b64_e32 v[128:129], 0xb6c
	v_mov_b64_e32 v[130:131], 0xb6b
	v_readlane_b32 s0, v254, 16
	s_nop 3
	s_lshl_b32 s0, s0, 4
	s_add_i32 s0, s0, 0x23800
	s_nop 1
	v_mov_b32_e32 v130, s0
	ds_read_b32 v128, v130 offset:8
	s_waitcnt lgkmcnt(0)
	v_add_u32_e32 v130, -1, v128
	v_add_u32_e32 v151, 0, v0
	v_add_u32_e32 v153, 0, v3
	s_mov_b32 s55, 0x3d010204
	s_mov_b32 s81, 0xc3e00000
	s_movk_i32 s82, 0x2b00
	v_mov_b32_e32 v159, 0x43e00000
	s_barrier
	s_branch .LBB0_213

.LBB0_229:
	v_readlane_b32 s0, v254, 16
	s_nop 3
	s_lshl_b32 s0, s0, 4
	s_add_i32 s0, s0, 0x23800
	s_nop 1
	v_mov_b32_e32 v0, s0
	ds_read_b64 v[0:1], v0
	s_waitcnt lgkmcnt(0)
	v_readfirstlane_b32 s0, v0
	v_readfirstlane_b32 s1, v1
	s_nop 3
	s_cmp_lg_u32 s0, 2
	s_cbranch_scc1 .Lsplit_tail_1
	s_sub_i32 s95, s95, s1
	s_nop 3
	v_writelane_b32 v254, s95, 22
	s_branch .Lsplit_post_1

.LBB0_233:
.Lsplit_post_1:
	v_readlane_b32 s0, v254, 16
	s_nop 3
	s_lshl_b32 s0, s0, 4
	s_add_i32 s0, s0, 0x23800
	s_nop 1
	v_mov_b32_e32 v0, s0
	ds_read_b32 v1, v0
	s_waitcnt lgkmcnt(0)
	v_readfirstlane_b32 s0, v1
	s_nop 3
	s_cmp_lg_u32 s0, 0
	s_cbranch_scc1 .Lsplit_go_1
	s_waitcnt vmcnt(0) lgkmcnt(0)
	s_barrier
	v_mov_b32_e32 v1, 2
	ds_write_b32 v0, v1
	v_mov_b32_e32 v1, 0xb6c
	ds_write_b32 v0, v1 offset:8
	ds_read_b32 v5, v0 offset:4
	s_waitcnt lgkmcnt(0)
	v_readlane_b32 s0, v254, 16
	s_nop 3
	s_lshl_b32 s0, s0, 10
	s_add_i32 s0, s0, 0x21400
	s_nop 1
	v_mov_b32_e32 v0, s0
	v_mbcnt_lo_u32_b32 v2, -1, 0
	v_mbcnt_hi_u32_b32 v2, -1, v2
	v_lshl_add_u32 v2, v2, 2, v0
	ds_read_b32 v254, v2 offset:512
	ds_read_b32 v255, v2 offset:768
	s_waitcnt lgkmcnt(0)
	ds_read_b32 v1, v0 offset:0
	s_waitcnt lgkmcnt(0)
	v_readfirstlane_b32 s0, v1
	ds_read_b32 v1, v0 offset:4
	s_waitcnt lgkmcnt(0)
	v_readfirstlane_b32 s1, v1
	ds_read_b32 v1, v0 offset:8
	s_waitcnt lgkmcnt(0)
	v_readfirstlane_b32 s2, v1
	ds_read_b32 v1, v0 offset:12
	s_waitcnt lgkmcnt(0)
	v_readfirstlane_b32 s3, v1
	ds_read_b32 v1, v0 offset:16
	s_waitcnt lgkmcnt(0)
	v_readfirstlane_b32 s4, v1
	ds_read_b32 v1, v0 offset:20
	s_waitcnt lgkmcnt(0)
	v_readfirstlane_b32 s5, v1
	ds_read_b32 v1, v0 offset:24
	s_waitcnt lgkmcnt(0)
	v_readfirstlane_b32 s6, v1
	ds_read_b32 v1, v0 offset:28
	s_waitcnt lgkmcnt(0)
	v_readfirstlane_b32 s7, v1
	ds_read_b32 v1, v0 offset:32
	s_waitcnt lgkmcnt(0)
	v_readfirstlane_b32 s8, v1
	ds_read_b32 v1, v0 offset:36
	s_waitcnt lgkmcnt(0)
	v_readfirstlane_b32 s9, v1
	ds_read_b32 v1, v0 offset:40
	s_waitcnt lgkmcnt(0)
	v_readfirstlane_b32 s10, v1
	ds_read_b32 v1, v0 offset:44
	s_waitcnt lgkmcnt(0)
	v_readfirstlane_b32 s11, v1
	ds_read_b32 v1, v0 offset:48
	s_waitcnt lgkmcnt(0)
	v_readfirstlane_b32 s12, v1
	ds_read_b32 v1, v0 offset:52
	s_waitcnt lgkmcnt(0)
	v_readfirstlane_b32 s13, v1
	ds_read_b32 v1, v0 offset:56
	s_waitcnt lgkmcnt(0)
	v_readfirstlane_b32 s14, v1
	ds_read_b32 v1, v0 offset:60
	s_waitcnt lgkmcnt(0)
	v_readfirstlane_b32 s15, v1
	ds_read_b32 v1, v0 offset:64
	s_waitcnt lgkmcnt(0)
	v_readfirstlane_b32 s16, v1
	ds_read_b32 v1, v0 offset:68
	s_waitcnt lgkmcnt(0)
	v_readfirstlane_b32 s17, v1
	ds_read_b32 v1, v0 offset:72
	s_waitcnt lgkmcnt(0)
	v_readfirstlane_b32 s18, v1
	ds_read_b32 v1, v0 offset:76
	s_waitcnt lgkmcnt(0)
	v_readfirstlane_b32 s19, v1
	ds_read_b32 v1, v0 offset:80
	s_waitcnt lgkmcnt(0)
	v_readfirstlane_b32 s20, v1
	ds_read_b32 v1, v0 offset:84
	s_waitcnt lgkmcnt(0)
	v_readfirstlane_b32 s21, v1
	ds_read_b32 v1, v0 offset:88
	s_waitcnt lgkmcnt(0)
	v_readfirstlane_b32 s22, v1
	ds_read_b32 v1, v0 offset:92
	s_waitcnt lgkmcnt(0)
	v_readfirstlane_b32 s23, v1
	ds_read_b32 v1, v0 offset:96
	s_waitcnt lgkmcnt(0)
	v_readfirstlane_b32 s24, v1
	ds_read_b32 v1, v0 offset:100
	s_waitcnt lgkmcnt(0)
	v_readfirstlane_b32 s25, v1
	ds_read_b32 v1, v0 offset:104
	s_waitcnt lgkmcnt(0)
	v_readfirstlane_b32 s26, v1
	ds_read_b32 v1, v0 offset:108
	s_waitcnt lgkmcnt(0)
	v_readfirstlane_b32 s27, v1
	ds_read_b32 v1, v0 offset:112
	s_waitcnt lgkmcnt(0)
	v_readfirstlane_b32 s28, v1
	ds_read_b32 v1, v0 offset:116
	s_waitcnt lgkmcnt(0)
	v_readfirstlane_b32 s29, v1
	ds_read_b32 v1, v0 offset:120
	s_waitcnt lgkmcnt(0)
	v_readfirstlane_b32 s30, v1
	ds_read_b32 v1, v0 offset:124
	s_waitcnt lgkmcnt(0)
	v_readfirstlane_b32 s31, v1
	ds_read_b32 v1, v0 offset:128
	s_waitcnt lgkmcnt(0)
	v_readfirstlane_b32 s32, v1
	ds_read_b32 v1, v0 offset:132
	s_waitcnt lgkmcnt(0)
	v_readfirstlane_b32 s33, v1
	ds_read_b32 v1, v0 offset:136
	s_waitcnt lgkmcnt(0)
	v_readfirstlane_b32 s34, v1
	ds_read_b32 v1, v0 offset:140
	s_waitcnt lgkmcnt(0)
	v_readfirstlane_b32 s35, v1
	ds_read_b32 v1, v0 offset:144
	s_waitcnt lgkmcnt(0)
	v_readfirstlane_b32 s36, v1
	ds_read_b32 v1, v0 offset:148
	s_waitcnt lgkmcnt(0)
	v_readfirstlane_b32 s37, v1
	ds_read_b32 v1, v0 offset:152
	s_waitcnt lgkmcnt(0)
	v_readfirstlane_b32 s38, v1
	ds_read_b32 v1, v0 offset:156
	s_waitcnt lgkmcnt(0)
	v_readfirstlane_b32 s39, v1
	ds_read_b32 v1, v0 offset:160
	s_waitcnt lgkmcnt(0)
	v_readfirstlane_b32 s40, v1
	ds_read_b32 v1, v0 offset:164
	s_waitcnt lgkmcnt(0)
	v_readfirstlane_b32 s41, v1
	ds_read_b32 v1, v0 offset:168
	s_waitcnt lgkmcnt(0)
	v_readfirstlane_b32 s42, v1
	ds_read_b32 v1, v0 offset:172
	s_waitcnt lgkmcnt(0)
	v_readfirstlane_b32 s43, v1
	ds_read_b32 v1, v0 offset:176
	s_waitcnt lgkmcnt(0)
	v_readfirstlane_b32 s44, v1
	ds_read_b32 v1, v0 offset:180
	s_waitcnt lgkmcnt(0)
	v_readfirstlane_b32 s45, v1
	ds_read_b32 v1, v0 offset:184
	s_waitcnt lgkmcnt(0)
	v_readfirstlane_b32 s46, v1
	ds_read_b32 v1, v0 offset:188
	s_waitcnt lgkmcnt(0)
	v_readfirstlane_b32 s47, v1
	ds_read_b32 v1, v0 offset:192
	s_waitcnt lgkmcnt(0)
	v_readfirstlane_b32 s48, v1
	ds_read_b32 v1, v0 offset:196
	s_waitcnt lgkmcnt(0)
	v_readfirstlane_b32 s49, v1
	ds_read_b32 v1, v0 offset:200
	s_waitcnt lgkmcnt(0)
	v_readfirstlane_b32 s50, v1
	ds_read_b32 v1, v0 offset:204
	s_waitcnt lgkmcnt(0)
	v_readfirstlane_b32 s51, v1
	ds_read_b32 v1, v0 offset:208
	s_waitcnt lgkmcnt(0)
	v_readfirstlane_b32 s52, v1
	ds_read_b32 v1, v0 offset:212
	s_waitcnt lgkmcnt(0)
	v_readfirstlane_b32 s53, v1
	ds_read_b32 v1, v0 offset:216
	s_waitcnt lgkmcnt(0)
	v_readfirstlane_b32 s54, v1
	ds_read_b32 v1, v0 offset:220
	s_waitcnt lgkmcnt(0)
	v_readfirstlane_b32 s55, v1
	ds_read_b32 v1, v0 offset:224
	s_waitcnt lgkmcnt(0)
	v_readfirstlane_b32 s56, v1
	ds_read_b32 v1, v0 offset:228
	s_waitcnt lgkmcnt(0)
	v_readfirstlane_b32 s57, v1
	ds_read_b32 v1, v0 offset:232
	s_waitcnt lgkmcnt(0)
	v_readfirstlane_b32 s58, v1
	ds_read_b32 v1, v0 offset:236
	s_waitcnt lgkmcnt(0)
	v_readfirstlane_b32 s59, v1
	ds_read_b32 v1, v0 offset:240
	s_waitcnt lgkmcnt(0)
	v_readfirstlane_b32 s60, v1
	ds_read_b32 v1, v0 offset:244
	s_waitcnt lgkmcnt(0)
	v_readfirstlane_b32 s61, v1
	ds_read_b32 v1, v0 offset:248
	s_waitcnt lgkmcnt(0)
	v_readfirstlane_b32 s62, v1
	ds_read_b32 v1, v0 offset:252
	s_waitcnt lgkmcnt(0)
	v_readfirstlane_b32 s63, v1
	ds_read_b32 v1, v0 offset:256
	s_waitcnt lgkmcnt(0)
	v_readfirstlane_b32 s64, v1
	ds_read_b32 v1, v0 offset:260
	s_waitcnt lgkmcnt(0)
	v_readfirstlane_b32 s65, v1
	ds_read_b32 v1, v0 offset:264
	s_waitcnt lgkmcnt(0)
	v_readfirstlane_b32 s66, v1
	ds_read_b32 v1, v0 offset:268
	s_waitcnt lgkmcnt(0)
	v_readfirstlane_b32 s67, v1
	ds_read_b32 v1, v0 offset:272
	s_waitcnt lgkmcnt(0)
	v_readfirstlane_b32 s68, v1
	ds_read_b32 v1, v0 offset:276
	s_waitcnt lgkmcnt(0)
	v_readfirstlane_b32 s69, v1
	ds_read_b32 v1, v0 offset:280
	s_waitcnt lgkmcnt(0)
	v_readfirstlane_b32 s70, v1
	ds_read_b32 v1, v0 offset:284
	s_waitcnt lgkmcnt(0)
	v_readfirstlane_b32 s71, v1
	ds_read_b32 v1, v0 offset:288
	s_waitcnt lgkmcnt(0)
	v_readfirstlane_b32 s72, v1
	ds_read_b32 v1, v0 offset:292
	s_waitcnt lgkmcnt(0)
	v_readfirstlane_b32 s73, v1
	ds_read_b32 v1, v0 offset:296
	s_waitcnt lgkmcnt(0)
	v_readfirstlane_b32 s74, v1
	ds_read_b32 v1, v0 offset:300
	s_waitcnt lgkmcnt(0)
	v_readfirstlane_b32 s75, v1
	ds_read_b32 v1, v0 offset:304
	s_waitcnt lgkmcnt(0)
	v_readfirstlane_b32 s76, v1
	ds_read_b32 v1, v0 offset:308
	s_waitcnt lgkmcnt(0)
	v_readfirstlane_b32 s77, v1
	ds_read_b32 v1, v0 offset:312
	s_waitcnt lgkmcnt(0)
	v_readfirstlane_b32 s78, v1
	ds_read_b32 v1, v0 offset:316
	s_waitcnt lgkmcnt(0)
	v_readfirstlane_b32 s79, v1
	ds_read_b32 v1, v0 offset:320
	s_waitcnt lgkmcnt(0)
	v_readfirstlane_b32 s80, v1
	ds_read_b32 v1, v0 offset:324
	s_waitcnt lgkmcnt(0)
	v_readfirstlane_b32 s81, v1
	ds_read_b32 v1, v0 offset:328
	s_waitcnt lgkmcnt(0)
	v_readfirstlane_b32 s82, v1
	ds_read_b32 v1, v0 offset:332
	s_waitcnt lgkmcnt(0)
	v_readfirstlane_b32 s83, v1
	ds_read_b32 v1, v0 offset:336
	s_waitcnt lgkmcnt(0)
	v_readfirstlane_b32 s84, v1
	ds_read_b32 v1, v0 offset:340
	s_waitcnt lgkmcnt(0)
	v_readfirstlane_b32 s85, v1
	ds_read_b32 v1, v0 offset:344
	s_waitcnt lgkmcnt(0)
	v_readfirstlane_b32 s86, v1
	ds_read_b32 v1, v0 offset:348
	s_waitcnt lgkmcnt(0)
	v_readfirstlane_b32 s87, v1
	ds_read_b32 v1, v0 offset:352
	s_waitcnt lgkmcnt(0)
	v_readfirstlane_b32 s88, v1
	ds_read_b32 v1, v0 offset:356
	s_waitcnt lgkmcnt(0)
	v_readfirstlane_b32 s89, v1
	ds_read_b32 v1, v0 offset:360
	s_waitcnt lgkmcnt(0)
	v_readfirstlane_b32 s90, v1
	ds_read_b32 v1, v0 offset:364
	s_waitcnt lgkmcnt(0)
	v_readfirstlane_b32 s91, v1
	ds_read_b32 v1, v0 offset:368
	s_waitcnt lgkmcnt(0)
	v_readfirstlane_b32 s92, v1
	ds_read_b32 v1, v0 offset:372
	s_waitcnt lgkmcnt(0)
	v_readfirstlane_b32 s93, v1
	ds_read_b32 v1, v0 offset:376
	s_waitcnt lgkmcnt(0)
	v_readfirstlane_b32 s94, v1
	ds_read_b32 v1, v0 offset:380
	s_waitcnt lgkmcnt(0)
	v_readfirstlane_b32 s95, v1
	ds_read_b32 v1, v0 offset:384
	s_waitcnt lgkmcnt(0)
	v_readfirstlane_b32 s96, v1
	ds_read_b32 v1, v0 offset:388
	s_waitcnt lgkmcnt(0)
	v_readfirstlane_b32 s97, v1
	ds_read_b32 v1, v0 offset:408
	s_waitcnt lgkmcnt(0)
	v_readfirstlane_b32 vcc_lo, v1
	ds_read_b32 v1, v0 offset:412
	s_waitcnt lgkmcnt(0)
	v_readfirstlane_b32 vcc_hi, v1
	v_readfirstlane_b32 s0, v5
	s_nop 3
	s_add_i32 s95, s95, s0
	s_nop 3
	v_writelane_b32 v254, s95, 22
	ds_read_b32 v1, v0 offset:0
	s_waitcnt lgkmcnt(0)
	v_readfirstlane_b32 s0, v1
	s_nop 4
	s_branch .Lsplit_enter_1
